# P6 tile epilogue: same store-drain fix as P5
# baseline (speedup 1.0000x reference)
.LBB0_719:
	s_or_b64 exec, exec, s[0:1]
	v_or_b32_e32 v144, 32, v174
	v_ashrrev_i32_e32 v145, 31, v144
	v_lshlrev_b64 v[142:143], 6, v[144:145]
	s_waitcnt lgkmcnt(0)
	v_lshl_add_u64 v[98:99], s[8:9], 0, v[142:143]
	global_load_dwordx4 v[146:149], v[98:99], off
	global_load_dwordx4 v[150:153], v[98:99], off offset:32
	global_load_dwordx4 v[154:157], v[98:99], off offset:16
	global_load_dwordx4 v[158:161], v[98:99], off offset:48
	v_lshlrev_b64 v[98:99], 11, v[144:145]
	v_lshl_add_u64 v[100:101], s[2:3], 0, v[98:99]
	v_lshl_add_u64 v[100:101], v[100:101], 0, v[176:177]
	global_load_dwordx4 v[162:165], v[100:101], off
	v_lshl_add_u64 v[98:99], s[10:11], 0, v[98:99]
	v_lshl_add_u64 v[98:99], v[98:99], 0, v[176:177]
	global_load_dwordx4 v[166:169], v[98:99], off
	v_or_b32_e32 v140, 48, v174
	v_ashrrev_i32_e32 v141, 31, v140
	v_lshlrev_b64 v[138:139], 6, v[140:141]
	v_lshlrev_b64 v[102:103], 11, v[140:141]
	v_lshl_add_u64 v[104:105], s[8:9], 0, v[138:139]
	v_lshl_add_u64 v[106:107], s[2:3], 0, v[102:103]
	v_lshl_add_u64 v[102:103], s[10:11], 0, v[102:103]
	global_load_dwordx4 v[114:117], v[104:105], off offset:48
	global_load_dwordx4 v[122:125], v[104:105], off offset:32
	global_load_dwordx4 v[126:129], v[104:105], off offset:16
	global_load_dwordx4 v[118:121], v[104:105], off
	v_lshl_add_u64 v[104:105], v[106:107], 0, v[176:177]
	v_lshl_add_u64 v[178:179], v[102:103], 0, v[176:177]
	global_load_dwordx4 v[134:137], v[100:101], off offset:256
	global_load_dwordx4 v[130:133], v[98:99], off offset:256
	global_load_dwordx4 v[110:113], v[104:105], off
	s_nop 0
	global_load_dwordx4 v[102:105], v[104:105], off offset:256
	s_nop 0
	global_load_dwordx4 v[106:109], v[178:179], off
	global_load_dwordx4 v[98:101], v[178:179], off offset:256
	s_waitcnt vmcnt(15)
	v_mov_b32_e32 v178, v148
	s_waitcnt vmcnt(14)
	v_mov_b32_e32 v179, v152
	v_mov_b32_e32 v152, v149
	s_waitcnt vmcnt(13)
	v_mov_b32_e32 v148, v154
	s_waitcnt vmcnt(12)
	v_mov_b32_e32 v149, v158
	v_mov_b32_e32 v158, v155
	v_mov_b32_e32 v154, v156
	v_mov_b32_e32 v155, v160
	v_mov_b32_e32 v160, v157
	v_mov_b32_e32 v156, v146
	v_mov_b32_e32 v157, v150
	v_mov_b32_e32 v150, v147
	v_pk_add_f32 v[146:147], v[178:179], v[152:153]
	v_pk_add_f32 v[148:149], v[148:149], v[158:159]
	v_pk_add_f32 v[152:153], v[154:155], v[160:161]
	v_pk_add_f32 v[150:151], v[156:157], v[150:151]
	v_pk_add_f32 v[148:149], v[148:149], v[152:153]
	v_pk_add_f32 v[146:147], v[150:151], v[146:147]
	s_waitcnt vmcnt(11)
	v_lshlrev_b32_e32 v154, 16, v162
	v_pk_add_f32 v[146:147], v[146:147], v[148:149]
	v_and_b32_e32 v155, 0xffff0000, v162
	v_add_f32_e32 v146, v146, v147
	v_fmamk_f32 v146, v146, 0x3a800000, v186
	v_mul_f32_e32 v147, 0x4b800000, v146
	v_cmp_gt_f32_e64 s[0:1], s45, v146
	v_lshlrev_b32_e32 v158, 16, v163
	v_and_b32_e32 v159, 0xffff0000, v163
	v_cndmask_b32_e64 v146, v146, v147, s[0:1]
	v_rsq_f32_e32 v148, v146
	v_lshlrev_b32_e32 v162, 16, v164
	v_and_b32_e32 v163, 0xffff0000, v164
	s_waitcnt vmcnt(10)
	v_lshlrev_b32_e32 v156, 16, v166
	v_mul_f32_e32 v149, 0x45800000, v148
	v_cndmask_b32_e64 v164, v148, v149, s[0:1]
	v_mul_f32_e32 v94, v94, v164
	v_mul_f32_e32 v95, v95, v164
	v_mul_f32_e32 v96, v96, v164
	v_mul_f32_e32 v97, v97, v164
	v_mul_f32_e32 v90, v90, v164
	v_mul_f32_e32 v91, v91, v164
	v_mul_f32_e32 v93, v93, v164
	v_mul_f32_e32 v94, 0xbfb8aa3b, v94
	v_mul_f32_e32 v95, 0xbfb8aa3b, v95
	v_mul_f32_e32 v88, v88, v164
	v_mul_f32_e32 v89, v89, v164
	v_mul_f32_e32 v96, 0xbfb8aa3b, v96
	v_mul_f32_e32 v97, 0xbfb8aa3b, v97
	v_mul_f32_e32 v90, 0xbfb8aa3b, v90
	v_mul_f32_e32 v91, 0xbfb8aa3b, v91
	v_mul_f32_e32 v148, 0xbfb8aa3b, v93
	v_exp_f32_e32 v93, v94
	v_exp_f32_e32 v94, v95
	v_mul_f32_e32 v88, 0xbfb8aa3b, v88
	v_mul_f32_e32 v89, 0xbfb8aa3b, v89
	v_mul_f32_e32 v82, v82, v164
	v_mul_f32_e32 v83, v83, v164
	v_exp_f32_e32 v95, v96
	v_exp_f32_e32 v96, v97
	v_exp_f32_e32 v90, v90
	v_exp_f32_e32 v91, v91
	v_exp_f32_e32 v88, v88
	v_exp_f32_e32 v89, v89
	v_mul_f32_e32 v82, 0xbfb8aa3b, v82
	v_mul_f32_e32 v83, 0xbfb8aa3b, v83
	v_mul_f32_e32 v92, v92, v164
	v_exp_f32_e32 v82, v82
	v_exp_f32_e32 v83, v83
	v_mul_f32_e32 v92, 0xbfb8aa3b, v92
	v_exp_f32_e32 v97, v92
	v_add_f32_e32 v92, 1.0, v93
	v_add_f32_e32 v93, 1.0, v94
	v_mul_f32_e32 v86, v86, v164
	v_mul_f32_e32 v87, v87, v164
	v_add_f32_e32 v94, 1.0, v95
	v_add_f32_e32 v95, 1.0, v96
	v_add_f32_e32 v96, 1.0, v90
	v_add_f32_e32 v149, 1.0, v91
	v_rcp_f32_e32 v90, v92
	v_rcp_f32_e32 v91, v93
	v_mul_f32_e32 v86, 0xbfb8aa3b, v86
	v_mul_f32_e32 v87, 0xbfb8aa3b, v87
	v_add_f32_e32 v88, 1.0, v88
	v_add_f32_e32 v89, 1.0, v89
	v_mul_f32_e32 v84, v84, v164
	v_mul_f32_e32 v85, v85, v164
	v_exp_f32_e32 v86, v86
	v_exp_f32_e32 v87, v87
	v_rcp_f32_e32 v88, v88
	v_rcp_f32_e32 v89, v89
	v_add_f32_e32 v82, 1.0, v82
	v_add_f32_e32 v83, 1.0, v83
	v_mul_f32_e32 v84, 0xbfb8aa3b, v84
	v_mul_f32_e32 v85, 0xbfb8aa3b, v85
	v_exp_f32_e32 v148, v148
	v_rcp_f32_e32 v82, v82
	v_rcp_f32_e32 v83, v83
	v_exp_f32_e32 v84, v84
	v_exp_f32_e32 v85, v85
	v_and_b32_e32 v157, 0xffff0000, v166
	v_pk_fma_f32 v[90:91], v[90:91], v[156:157], v[154:155]
	s_waitcnt vmcnt(5)
	v_lshlrev_b32_e32 v154, 16, v134
	v_and_b32_e32 v155, 0xffff0000, v134
	s_waitcnt vmcnt(4)
	v_lshlrev_b32_e32 v156, 16, v130
	v_and_b32_e32 v157, 0xffff0000, v130
	v_lshlrev_b32_e32 v134, 16, v135
	v_and_b32_e32 v135, 0xffff0000, v135
	v_lshlrev_b32_e32 v130, 16, v131
	v_and_b32_e32 v131, 0xffff0000, v131
	v_add_f32_e32 v86, 1.0, v86
	v_add_f32_e32 v87, 1.0, v87
	v_pk_fma_f32 v[88:89], v[88:89], v[130:131], v[134:135]
	v_lshlrev_b32_e32 v130, 16, v136
	v_and_b32_e32 v131, 0xffff0000, v136
	v_lshlrev_b32_e32 v134, 16, v132
	v_and_b32_e32 v135, 0xffff0000, v132
	v_rcp_f32_e32 v92, v94
	v_rcp_f32_e32 v93, v95
	v_rcp_f32_e32 v94, v96
	v_rcp_f32_e32 v95, v149
	v_add_f32_e32 v96, 1.0, v97
	v_add_f32_e32 v97, 1.0, v148
	v_rcp_f32_e32 v86, v86
	v_rcp_f32_e32 v87, v87
	v_pk_fma_f32 v[130:131], v[82:83], v[134:135], v[130:131]
	v_add_f32_e32 v82, 1.0, v84
	v_add_f32_e32 v83, 1.0, v85
	v_rcp_f32_e32 v96, v96
	v_rcp_f32_e32 v97, v97
	v_rcp_f32_e32 v82, v82
	v_rcp_f32_e32 v83, v83
	v_lshlrev_b32_e32 v146, 16, v168
	v_and_b32_e32 v147, 0xffff0000, v168
	v_pk_fma_f32 v[94:95], v[94:95], v[146:147], v[162:163]
	v_lshlrev_b32_e32 v146, 16, v165
	v_and_b32_e32 v147, 0xffff0000, v165
	v_lshlrev_b32_e32 v148, 16, v169
	v_and_b32_e32 v149, 0xffff0000, v169
	v_pk_fma_f32 v[86:87], v[86:87], v[156:157], v[154:155]
	v_lshlrev_b32_e32 v84, 16, v137
	v_and_b32_e32 v85, 0xffff0000, v137
	v_lshlrev_b32_e32 v132, 16, v133
	v_and_b32_e32 v133, 0xffff0000, v133
	v_lshlrev_b32_e32 v160, 16, v167
	v_and_b32_e32 v161, 0xffff0000, v167
	v_pk_fma_f32 v[96:97], v[96:97], v[148:149], v[146:147]
	v_pk_fma_f32 v[132:133], v[82:83], v[132:133], v[84:85]
	v_pk_mul_f32 v[82:83], v[86:87], v[86:87]
	v_pk_mul_f32 v[84:85], v[88:89], v[88:89]
	v_pk_fma_f32 v[92:93], v[92:93], v[160:161], v[158:159]
	v_pk_mul_f32 v[150:151], v[94:95], v[94:95]
	v_pk_mul_f32 v[152:153], v[96:97], v[96:97]
	v_add_f32_e32 v84, v84, v85
	v_add_f32_e32 v82, v82, v83
	v_pk_mul_f32 v[146:147], v[90:91], v[90:91]
	v_pk_mul_f32 v[148:149], v[92:93], v[92:93]
	v_pk_mul_f32 v[134:135], v[130:131], v[130:131]
	v_pk_mul_f32 v[136:137], v[132:133], v[132:133]
	v_add_f32_e32 v82, v82, v84
	v_add_f32_e32 v83, v152, v153
	v_add_f32_e32 v84, v150, v151
	v_add_f32_e32 v136, v136, v137
	v_add_f32_e32 v134, v134, v135
	v_add_f32_e32 v83, v84, v83
	v_add_f32_e32 v84, v148, v149
	v_add_f32_e32 v85, v146, v147
	v_add_f32_e32 v134, v134, v136
	v_add_f32_e32 v84, v85, v84
	v_add_f32_e32 v82, v82, v134
	v_add_f32_e32 v83, v84, v83
	v_add_f32_e32 v134, v83, v82
	ds_bpermute_b32 v135, v188, v134
	v_lshlrev_b64 v[82:83], 12, v[144:145]
	v_lshl_add_u64 v[82:83], s[74:75], 0, v[82:83]
	v_lshl_add_u64 v[84:85], v[172:173], 2, v[82:83]
	s_waitcnt vmcnt(0)
	global_store_dwordx4 v[84:85], v[90:93], off
	global_store_dwordx4 v[84:85], v[94:97], off offset:16
	global_store_dwordx4 v[84:85], v[86:89], off offset:512
	global_store_dwordx4 v[84:85], v[130:133], off offset:528
	s_waitcnt lgkmcnt(0)
	v_add_f32_e32 v82, v134, v135
	ds_bpermute_b32 v83, v170, v82
	s_and_saveexec_b64 s[0:1], vcc
	s_cbranch_execz .LBB0_721
	v_lshl_add_u64 v[84:85], s[6:7], 0, v[142:143]
	s_lshl_b32 s12, s34, 2
	v_lshl_add_u64 v[84:85], v[84:85], 0, s[12:13]
	s_waitcnt lgkmcnt(0)
	v_add_f32_e32 v82, v82, v83
	global_store_dword v[84:85], v82, off
.LBB0_721:
	s_or_b64 exec, exec, s[0:1]
	s_waitcnt lgkmcnt(0)
	v_add_f32_e32 v83, v126, v127
	v_add_f32_e32 v84, v128, v129
	v_add_f32_e32 v83, v83, v84
	v_add_f32_e32 v84, v122, v123
	v_add_f32_e32 v85, v124, v125
	v_add_f32_e32 v84, v84, v85
	v_add_f32_e32 v85, v114, v115
	v_add_f32_e32 v86, v116, v117
	v_add_f32_e32 v85, v85, v86
	v_add_f32_e32 v82, v120, v121
	v_add_f32_e32 v84, v84, v85
	v_add_f32_e32 v85, v118, v119
	v_add_f32_e32 v82, v85, v82
	v_add_f32_e32 v82, v82, v83
	v_add_f32_e32 v82, v82, v84
	v_fmamk_f32 v82, v82, 0x3a800000, v186
	v_mul_f32_e32 v83, 0x4b800000, v82
	v_cmp_gt_f32_e64 s[0:1], s45, v82
	v_lshlrev_b32_e32 v84, 16, v106
	v_and_b32_e32 v85, 0xffff0000, v106
	v_cndmask_b32_e64 v82, v82, v83, s[0:1]
	v_rsq_f32_e32 v82, v82
	s_nop 0
	v_mul_f32_e32 v83, 0x45800000, v82
	v_cndmask_b32_e64 v94, v82, v83, s[0:1]
	v_mul_f32_e32 v78, v78, v94
	v_mul_f32_e32 v79, v79, v94
	v_mul_f32_e32 v78, 0xbfb8aa3b, v78
	v_mul_f32_e32 v79, 0xbfb8aa3b, v79
	v_mul_f32_e32 v80, v80, v94
	v_mul_f32_e32 v81, v81, v94
	v_exp_f32_e32 v78, v78
	v_exp_f32_e32 v79, v79
	v_mul_f32_e32 v80, 0xbfb8aa3b, v80
	v_mul_f32_e32 v81, 0xbfb8aa3b, v81
	v_mul_f32_e32 v74, v74, v94
	v_mul_f32_e32 v75, v75, v94
	v_exp_f32_e32 v80, v80
	v_exp_f32_e32 v81, v81
	v_mul_f32_e32 v74, 0xbfb8aa3b, v74
	v_mul_f32_e32 v75, 0xbfb8aa3b, v75
	v_mul_f32_e32 v76, v76, v94
	v_mul_f32_e32 v77, v77, v94
	v_exp_f32_e32 v74, v74
	v_exp_f32_e32 v75, v75
	v_mul_f32_e32 v76, 0xbfb8aa3b, v76
	v_mul_f32_e32 v77, 0xbfb8aa3b, v77
	v_mul_f32_e32 v70, v70, v94
	v_mul_f32_e32 v71, v71, v94
	v_exp_f32_e32 v76, v76
	v_exp_f32_e32 v77, v77
	v_mul_f32_e32 v70, 0xbfb8aa3b, v70
	v_mul_f32_e32 v71, 0xbfb8aa3b, v71
	v_mul_f32_e32 v72, v72, v94
	v_mul_f32_e32 v73, v73, v94
	v_add_f32_e32 v78, 1.0, v78
	v_add_f32_e32 v79, 1.0, v79
	v_exp_f32_e32 v70, v70
	v_exp_f32_e32 v71, v71
	v_mul_f32_e32 v72, 0xbfb8aa3b, v72
	v_mul_f32_e32 v73, 0xbfb8aa3b, v73
	v_mul_f32_e32 v66, v66, v94
	v_mul_f32_e32 v67, v67, v94
	v_rcp_f32_e32 v78, v78
	v_rcp_f32_e32 v79, v79
	v_add_f32_e32 v80, 1.0, v80
	v_add_f32_e32 v81, 1.0, v81
	v_exp_f32_e32 v72, v72
	v_exp_f32_e32 v73, v73
	v_mul_f32_e32 v66, 0xbfb8aa3b, v66
	v_mul_f32_e32 v67, 0xbfb8aa3b, v67
	v_rcp_f32_e32 v80, v80
	v_rcp_f32_e32 v81, v81
	v_add_f32_e32 v74, 1.0, v74
	v_add_f32_e32 v75, 1.0, v75
	v_exp_f32_e32 v66, v66
	v_exp_f32_e32 v67, v67
	v_rcp_f32_e32 v74, v74
	v_rcp_f32_e32 v75, v75
	v_add_f32_e32 v76, 1.0, v76
	v_add_f32_e32 v77, 1.0, v77
	v_lshlrev_b32_e32 v82, 16, v110
	v_and_b32_e32 v83, 0xffff0000, v110
	v_rcp_f32_e32 v76, v76
	v_rcp_f32_e32 v77, v77
	v_add_f32_e32 v70, 1.0, v70
	v_add_f32_e32 v71, 1.0, v71
	v_pk_fma_f32 v[78:79], v[78:79], v[84:85], v[82:83]
	v_lshlrev_b32_e32 v82, 16, v111
	v_and_b32_e32 v83, 0xffff0000, v111
	v_lshlrev_b32_e32 v84, 16, v107
	v_and_b32_e32 v85, 0xffff0000, v107
	v_rcp_f32_e32 v70, v70
	v_rcp_f32_e32 v71, v71
	v_add_f32_e32 v72, 1.0, v72
	v_add_f32_e32 v73, 1.0, v73
	v_mul_f32_e32 v68, v68, v94
	v_mul_f32_e32 v69, v69, v94
	v_pk_fma_f32 v[80:81], v[80:81], v[84:85], v[82:83]
	v_lshlrev_b32_e32 v82, 16, v112
	v_and_b32_e32 v83, 0xffff0000, v112
	v_lshlrev_b32_e32 v84, 16, v108
	v_and_b32_e32 v85, 0xffff0000, v108
	v_rcp_f32_e32 v72, v72
	v_rcp_f32_e32 v73, v73
	v_add_f32_e32 v66, 1.0, v66
	v_add_f32_e32 v67, 1.0, v67
	v_mul_f32_e32 v68, 0xbfb8aa3b, v68
	v_mul_f32_e32 v69, 0xbfb8aa3b, v69
	v_pk_fma_f32 v[74:75], v[74:75], v[84:85], v[82:83]
	v_lshlrev_b32_e32 v82, 16, v113
	v_and_b32_e32 v83, 0xffff0000, v113
	v_lshlrev_b32_e32 v84, 16, v109
	v_and_b32_e32 v85, 0xffff0000, v109
	v_rcp_f32_e32 v66, v66
	v_rcp_f32_e32 v67, v67
	v_exp_f32_e32 v68, v68
	v_exp_f32_e32 v69, v69
	v_pk_fma_f32 v[76:77], v[76:77], v[84:85], v[82:83]
	v_lshlrev_b32_e32 v82, 16, v102
	v_and_b32_e32 v83, 0xffff0000, v102
	v_lshlrev_b32_e32 v84, 16, v98
	v_and_b32_e32 v85, 0xffff0000, v98
	v_pk_fma_f32 v[70:71], v[70:71], v[84:85], v[82:83]
	v_lshlrev_b32_e32 v82, 16, v103
	v_and_b32_e32 v83, 0xffff0000, v103
	v_lshlrev_b32_e32 v84, 16, v99
	v_and_b32_e32 v85, 0xffff0000, v99
	v_pk_fma_f32 v[72:73], v[72:73], v[84:85], v[82:83]
	v_lshlrev_b32_e32 v82, 16, v104
	v_and_b32_e32 v83, 0xffff0000, v104
	v_lshlrev_b32_e32 v84, 16, v100
	v_and_b32_e32 v85, 0xffff0000, v100
	v_pk_fma_f32 v[82:83], v[66:67], v[84:85], v[82:83]
	v_add_f32_e32 v66, 1.0, v68
	v_add_f32_e32 v67, 1.0, v69
	v_rcp_f32_e32 v66, v66
	v_rcp_f32_e32 v67, v67
	v_lshlrev_b32_e32 v68, 16, v105
	v_and_b32_e32 v69, 0xffff0000, v105
	v_lshlrev_b32_e32 v84, 16, v101
	v_and_b32_e32 v85, 0xffff0000, v101
	v_pk_fma_f32 v[84:85], v[66:67], v[84:85], v[68:69]
	v_pk_mul_f32 v[66:67], v[70:71], v[70:71]
	v_pk_mul_f32 v[68:69], v[72:73], v[72:73]
	v_pk_mul_f32 v[90:91], v[74:75], v[74:75]
	v_pk_mul_f32 v[92:93], v[76:77], v[76:77]
	v_add_f32_e32 v68, v68, v69
	v_add_f32_e32 v66, v66, v67
	v_pk_mul_f32 v[86:87], v[78:79], v[78:79]
	v_pk_mul_f32 v[88:89], v[80:81], v[80:81]
	v_pk_mul_f32 v[94:95], v[82:83], v[82:83]
	v_pk_mul_f32 v[96:97], v[84:85], v[84:85]
	v_add_f32_e32 v66, v66, v68
	v_add_f32_e32 v67, v92, v93
	v_add_f32_e32 v68, v90, v91
	v_add_f32_e32 v96, v96, v97
	v_add_f32_e32 v94, v94, v95
	v_add_f32_e32 v67, v68, v67
	v_add_f32_e32 v68, v88, v89
	v_add_f32_e32 v69, v86, v87
	v_add_f32_e32 v94, v94, v96
	v_add_f32_e32 v68, v69, v68
	v_add_f32_e32 v66, v66, v94
	v_add_f32_e32 v67, v68, v67
	v_add_f32_e32 v86, v67, v66
	ds_bpermute_b32 v87, v188, v86
	v_lshlrev_b64 v[66:67], 10, v[140:141]
	v_lshl_add_u64 v[66:67], v[66:67], 2, s[74:75]
	v_lshl_add_u64 v[68:69], v[172:173], 2, v[66:67]
	global_store_dwordx4 v[68:69], v[78:81], off
	global_store_dwordx4 v[68:69], v[74:77], off offset:16
	global_store_dwordx4 v[68:69], v[70:73], off offset:512
	global_store_dwordx4 v[68:69], v[82:85], off offset:528
	s_waitcnt lgkmcnt(0)
	v_add_f32_e32 v66, v86, v87
	ds_bpermute_b32 v67, v170, v66
	s_and_saveexec_b64 s[0:1], vcc
	s_cbranch_execz .LBB0_723
	v_lshl_add_u64 v[68:69], s[6:7], 0, v[138:139]
	s_lshl_b32 s12, s34, 2
	v_lshl_add_u64 v[68:69], v[68:69], 0, s[12:13]
	s_waitcnt lgkmcnt(0)
	v_add_f32_e32 v66, v66, v67
	global_store_dword v[68:69], v66, off
.LBB0_723:
	s_or_b64 exec, exec, s[0:1]
	v_add_u32_e32 v112, 0x80, v174
	v_ashrrev_i32_e32 v113, 31, v112
	v_lshlrev_b64 v[110:111], 6, v[112:113]
	s_waitcnt lgkmcnt(0)
	v_lshl_add_u64 v[66:67], s[8:9], 0, v[110:111]
	global_load_dwordx4 v[114:117], v[66:67], off
	global_load_dwordx4 v[118:121], v[66:67], off offset:32
	global_load_dwordx4 v[122:125], v[66:67], off offset:16
	global_load_dwordx4 v[126:129], v[66:67], off offset:48
	v_lshlrev_b64 v[66:67], 11, v[112:113]
	v_lshl_add_u64 v[68:69], s[2:3], 0, v[66:67]
	v_lshl_add_u64 v[68:69], v[68:69], 0, v[176:177]
	global_load_dwordx4 v[130:133], v[68:69], off
	v_lshl_add_u64 v[66:67], s[10:11], 0, v[66:67]
	v_lshl_add_u64 v[66:67], v[66:67], 0, v[176:177]
	global_load_dwordx4 v[134:137], v[66:67], off
	v_add_u32_e32 v108, 0x90, v174
	v_ashrrev_i32_e32 v109, 31, v108
	v_lshlrev_b64 v[106:107], 6, v[108:109]
	v_lshlrev_b64 v[70:71], 11, v[108:109]
	v_lshl_add_u64 v[72:73], s[8:9], 0, v[106:107]
	v_lshl_add_u64 v[74:75], s[2:3], 0, v[70:71]
	v_lshl_add_u64 v[70:71], s[10:11], 0, v[70:71]
	global_load_dwordx4 v[82:85], v[72:73], off offset:48
	global_load_dwordx4 v[90:93], v[72:73], off offset:32
	global_load_dwordx4 v[94:97], v[72:73], off offset:16
	global_load_dwordx4 v[86:89], v[72:73], off
	v_lshl_add_u64 v[72:73], v[74:75], 0, v[176:177]
	v_lshl_add_u64 v[138:139], v[70:71], 0, v[176:177]
	global_load_dwordx4 v[102:105], v[68:69], off offset:256
	global_load_dwordx4 v[98:101], v[66:67], off offset:256
	global_load_dwordx4 v[78:81], v[72:73], off
	s_nop 0
	global_load_dwordx4 v[70:73], v[72:73], off offset:256
	s_nop 0
	global_load_dwordx4 v[74:77], v[138:139], off
	global_load_dwordx4 v[66:69], v[138:139], off offset:256
	s_waitcnt vmcnt(15)
	v_mov_b32_e32 v138, v116
	s_waitcnt vmcnt(14)
	v_mov_b32_e32 v139, v120
	v_mov_b32_e32 v120, v117
	s_waitcnt vmcnt(13)
	v_mov_b32_e32 v116, v122
	s_waitcnt vmcnt(12)
	v_mov_b32_e32 v117, v126
	v_mov_b32_e32 v126, v123
	v_mov_b32_e32 v122, v124
	v_mov_b32_e32 v123, v128
	v_mov_b32_e32 v128, v125
	v_mov_b32_e32 v124, v114
	v_mov_b32_e32 v125, v118
	v_mov_b32_e32 v118, v115
	v_pk_add_f32 v[114:115], v[138:139], v[120:121]
	v_pk_add_f32 v[116:117], v[116:117], v[126:127]
	v_pk_add_f32 v[120:121], v[122:123], v[128:129]
	v_pk_add_f32 v[118:119], v[124:125], v[118:119]
	v_pk_add_f32 v[116:117], v[116:117], v[120:121]
	v_pk_add_f32 v[114:115], v[118:119], v[114:115]
	s_waitcnt vmcnt(11)
	v_lshlrev_b32_e32 v122, 16, v130
	v_pk_add_f32 v[114:115], v[114:115], v[116:117]
	v_and_b32_e32 v123, 0xffff0000, v130
	v_add_f32_e32 v114, v114, v115
	v_fmamk_f32 v114, v114, 0x3a800000, v186
	v_mul_f32_e32 v115, 0x4b800000, v114
	v_cmp_gt_f32_e64 s[0:1], s45, v114
	v_lshlrev_b32_e32 v126, 16, v131
	v_and_b32_e32 v127, 0xffff0000, v131
	v_cndmask_b32_e64 v114, v114, v115, s[0:1]
	v_rsq_f32_e32 v116, v114
	v_lshlrev_b32_e32 v130, 16, v132
	v_and_b32_e32 v131, 0xffff0000, v132
	s_waitcnt vmcnt(10)
	v_lshlrev_b32_e32 v124, 16, v134
	v_mul_f32_e32 v117, 0x45800000, v116
	v_cndmask_b32_e64 v132, v116, v117, s[0:1]
	v_mul_f32_e32 v62, v62, v132
	v_mul_f32_e32 v63, v63, v132
	v_mul_f32_e32 v64, v64, v132
	v_mul_f32_e32 v65, v65, v132
	v_mul_f32_e32 v58, v58, v132
	v_mul_f32_e32 v59, v59, v132
	v_mul_f32_e32 v61, v61, v132
	v_mul_f32_e32 v62, 0xbfb8aa3b, v62
	v_mul_f32_e32 v63, 0xbfb8aa3b, v63
	v_mul_f32_e32 v56, v56, v132
	v_mul_f32_e32 v57, v57, v132
	v_mul_f32_e32 v64, 0xbfb8aa3b, v64
	v_mul_f32_e32 v65, 0xbfb8aa3b, v65
	v_mul_f32_e32 v58, 0xbfb8aa3b, v58
	v_mul_f32_e32 v59, 0xbfb8aa3b, v59
	v_mul_f32_e32 v116, 0xbfb8aa3b, v61
	v_exp_f32_e32 v61, v62
	v_exp_f32_e32 v62, v63
	v_mul_f32_e32 v56, 0xbfb8aa3b, v56
	v_mul_f32_e32 v57, 0xbfb8aa3b, v57
	v_mul_f32_e32 v50, v50, v132
	v_mul_f32_e32 v51, v51, v132
	v_exp_f32_e32 v63, v64
	v_exp_f32_e32 v64, v65
	v_exp_f32_e32 v58, v58
	v_exp_f32_e32 v59, v59
	v_exp_f32_e32 v56, v56
	v_exp_f32_e32 v57, v57
	v_mul_f32_e32 v50, 0xbfb8aa3b, v50
	v_mul_f32_e32 v51, 0xbfb8aa3b, v51
	v_mul_f32_e32 v60, v60, v132
	v_exp_f32_e32 v50, v50
	v_exp_f32_e32 v51, v51
	v_mul_f32_e32 v60, 0xbfb8aa3b, v60
	v_exp_f32_e32 v65, v60
	v_add_f32_e32 v60, 1.0, v61
	v_add_f32_e32 v61, 1.0, v62
	v_mul_f32_e32 v54, v54, v132
	v_mul_f32_e32 v55, v55, v132
	v_add_f32_e32 v62, 1.0, v63
	v_add_f32_e32 v63, 1.0, v64
	v_add_f32_e32 v64, 1.0, v58
	v_add_f32_e32 v117, 1.0, v59
	v_rcp_f32_e32 v58, v60
	v_rcp_f32_e32 v59, v61
	v_mul_f32_e32 v54, 0xbfb8aa3b, v54
	v_mul_f32_e32 v55, 0xbfb8aa3b, v55
	v_add_f32_e32 v56, 1.0, v56
	v_add_f32_e32 v57, 1.0, v57
	v_mul_f32_e32 v52, v52, v132
	v_mul_f32_e32 v53, v53, v132
	v_exp_f32_e32 v54, v54
	v_exp_f32_e32 v55, v55
	v_rcp_f32_e32 v56, v56
	v_rcp_f32_e32 v57, v57
	v_add_f32_e32 v50, 1.0, v50
	v_add_f32_e32 v51, 1.0, v51
	v_mul_f32_e32 v52, 0xbfb8aa3b, v52
	v_mul_f32_e32 v53, 0xbfb8aa3b, v53
	v_exp_f32_e32 v116, v116
	v_rcp_f32_e32 v50, v50
	v_rcp_f32_e32 v51, v51
	v_exp_f32_e32 v52, v52
	v_exp_f32_e32 v53, v53
	v_and_b32_e32 v125, 0xffff0000, v134
	v_pk_fma_f32 v[58:59], v[58:59], v[124:125], v[122:123]
	s_waitcnt vmcnt(5)
	v_lshlrev_b32_e32 v122, 16, v102
	v_and_b32_e32 v123, 0xffff0000, v102
	s_waitcnt vmcnt(4)
	v_lshlrev_b32_e32 v124, 16, v98
	v_and_b32_e32 v125, 0xffff0000, v98
	v_lshlrev_b32_e32 v102, 16, v103
	v_and_b32_e32 v103, 0xffff0000, v103
	v_lshlrev_b32_e32 v98, 16, v99
	v_and_b32_e32 v99, 0xffff0000, v99
	v_add_f32_e32 v54, 1.0, v54
	v_add_f32_e32 v55, 1.0, v55
	v_pk_fma_f32 v[56:57], v[56:57], v[98:99], v[102:103]
	v_lshlrev_b32_e32 v98, 16, v104
	v_and_b32_e32 v99, 0xffff0000, v104
	v_lshlrev_b32_e32 v102, 16, v100
	v_and_b32_e32 v103, 0xffff0000, v100
	v_rcp_f32_e32 v60, v62
	v_rcp_f32_e32 v61, v63
	v_rcp_f32_e32 v62, v64
	v_rcp_f32_e32 v63, v117
	v_add_f32_e32 v64, 1.0, v65
	v_add_f32_e32 v65, 1.0, v116
	v_rcp_f32_e32 v54, v54
	v_rcp_f32_e32 v55, v55
	v_pk_fma_f32 v[98:99], v[50:51], v[102:103], v[98:99]
	v_add_f32_e32 v50, 1.0, v52
	v_add_f32_e32 v51, 1.0, v53
	v_rcp_f32_e32 v64, v64
	v_rcp_f32_e32 v65, v65
	v_rcp_f32_e32 v50, v50
	v_rcp_f32_e32 v51, v51
	v_lshlrev_b32_e32 v114, 16, v136
	v_and_b32_e32 v115, 0xffff0000, v136
	v_pk_fma_f32 v[62:63], v[62:63], v[114:115], v[130:131]
	v_lshlrev_b32_e32 v114, 16, v133
	v_and_b32_e32 v115, 0xffff0000, v133
	v_lshlrev_b32_e32 v116, 16, v137
	v_and_b32_e32 v117, 0xffff0000, v137
	v_pk_fma_f32 v[54:55], v[54:55], v[124:125], v[122:123]
	v_lshlrev_b32_e32 v52, 16, v105
	v_and_b32_e32 v53, 0xffff0000, v105
	v_lshlrev_b32_e32 v100, 16, v101
	v_and_b32_e32 v101, 0xffff0000, v101
	v_lshlrev_b32_e32 v128, 16, v135
	v_and_b32_e32 v129, 0xffff0000, v135
	v_pk_fma_f32 v[64:65], v[64:65], v[116:117], v[114:115]
	v_pk_fma_f32 v[100:101], v[50:51], v[100:101], v[52:53]
	v_pk_mul_f32 v[50:51], v[54:55], v[54:55]
	v_pk_mul_f32 v[52:53], v[56:57], v[56:57]
	v_pk_fma_f32 v[60:61], v[60:61], v[128:129], v[126:127]
	v_pk_mul_f32 v[118:119], v[62:63], v[62:63]
	v_pk_mul_f32 v[120:121], v[64:65], v[64:65]
	v_add_f32_e32 v52, v52, v53
	v_add_f32_e32 v50, v50, v51
	v_pk_mul_f32 v[114:115], v[58:59], v[58:59]
	v_pk_mul_f32 v[116:117], v[60:61], v[60:61]
	v_pk_mul_f32 v[102:103], v[98:99], v[98:99]
	v_pk_mul_f32 v[104:105], v[100:101], v[100:101]
	v_add_f32_e32 v50, v50, v52
	v_add_f32_e32 v51, v120, v121
	v_add_f32_e32 v52, v118, v119
	v_add_f32_e32 v104, v104, v105
	v_add_f32_e32 v102, v102, v103
	v_add_f32_e32 v51, v52, v51
	v_add_f32_e32 v52, v116, v117
	v_add_f32_e32 v53, v114, v115
	v_add_f32_e32 v102, v102, v104
	v_add_f32_e32 v52, v53, v52
	v_add_f32_e32 v50, v50, v102
	v_add_f32_e32 v51, v52, v51
	v_add_f32_e32 v102, v51, v50
	ds_bpermute_b32 v103, v188, v102
	v_lshlrev_b64 v[50:51], 12, v[112:113]
	v_lshl_add_u64 v[50:51], s[74:75], 0, v[50:51]
	v_lshl_add_u64 v[52:53], v[172:173], 2, v[50:51]
	s_waitcnt vmcnt(0)
	global_store_dwordx4 v[52:53], v[58:61], off
	global_store_dwordx4 v[52:53], v[62:65], off offset:16
	global_store_dwordx4 v[52:53], v[54:57], off offset:512
	global_store_dwordx4 v[52:53], v[98:101], off offset:528
	s_waitcnt lgkmcnt(0)
	v_add_f32_e32 v50, v102, v103
	ds_bpermute_b32 v51, v170, v50
	s_and_saveexec_b64 s[0:1], vcc
	s_cbranch_execz .LBB0_725
	v_lshl_add_u64 v[52:53], s[6:7], 0, v[110:111]
	s_lshl_b32 s12, s34, 2
	v_lshl_add_u64 v[52:53], v[52:53], 0, s[12:13]
	s_waitcnt lgkmcnt(0)
	v_add_f32_e32 v50, v50, v51
	global_store_dword v[52:53], v50, off
.LBB0_725:
	s_or_b64 exec, exec, s[0:1]
	s_waitcnt lgkmcnt(0)
	v_add_f32_e32 v51, v94, v95
	v_add_f32_e32 v52, v96, v97
	v_add_f32_e32 v51, v51, v52
	v_add_f32_e32 v52, v90, v91
	v_add_f32_e32 v53, v92, v93
	v_add_f32_e32 v52, v52, v53
	v_add_f32_e32 v53, v82, v83
	v_add_f32_e32 v54, v84, v85
	v_add_f32_e32 v53, v53, v54
	v_add_f32_e32 v50, v88, v89
	v_add_f32_e32 v52, v52, v53
	v_add_f32_e32 v53, v86, v87
	v_add_f32_e32 v50, v53, v50
	v_add_f32_e32 v50, v50, v51
	v_add_f32_e32 v50, v50, v52
	v_fmamk_f32 v50, v50, 0x3a800000, v186
	v_mul_f32_e32 v51, 0x4b800000, v50
	v_cmp_gt_f32_e64 s[0:1], s45, v50
	v_lshlrev_b32_e32 v52, 16, v74
	v_and_b32_e32 v53, 0xffff0000, v74
	v_cndmask_b32_e64 v50, v50, v51, s[0:1]
	v_rsq_f32_e32 v50, v50
	s_nop 0
	v_mul_f32_e32 v51, 0x45800000, v50
	v_cndmask_b32_e64 v62, v50, v51, s[0:1]
	v_mul_f32_e32 v46, v46, v62
	v_mul_f32_e32 v47, v47, v62
	v_mul_f32_e32 v46, 0xbfb8aa3b, v46
	v_mul_f32_e32 v47, 0xbfb8aa3b, v47
	v_mul_f32_e32 v48, v48, v62
	v_mul_f32_e32 v49, v49, v62
	v_exp_f32_e32 v46, v46
	v_exp_f32_e32 v47, v47
	v_mul_f32_e32 v48, 0xbfb8aa3b, v48
	v_mul_f32_e32 v49, 0xbfb8aa3b, v49
	v_mul_f32_e32 v42, v42, v62
	v_mul_f32_e32 v43, v43, v62
	v_exp_f32_e32 v48, v48
	v_exp_f32_e32 v49, v49
	v_mul_f32_e32 v42, 0xbfb8aa3b, v42
	v_mul_f32_e32 v43, 0xbfb8aa3b, v43
	v_mul_f32_e32 v44, v44, v62
	v_mul_f32_e32 v45, v45, v62
	v_exp_f32_e32 v42, v42
	v_exp_f32_e32 v43, v43
	v_mul_f32_e32 v44, 0xbfb8aa3b, v44
	v_mul_f32_e32 v45, 0xbfb8aa3b, v45
	v_mul_f32_e32 v38, v38, v62
	v_mul_f32_e32 v39, v39, v62
	v_exp_f32_e32 v44, v44
	v_exp_f32_e32 v45, v45
	v_mul_f32_e32 v38, 0xbfb8aa3b, v38
	v_mul_f32_e32 v39, 0xbfb8aa3b, v39
	v_mul_f32_e32 v40, v40, v62
	v_mul_f32_e32 v41, v41, v62
	v_add_f32_e32 v46, 1.0, v46
	v_add_f32_e32 v47, 1.0, v47
	v_exp_f32_e32 v38, v38
	v_exp_f32_e32 v39, v39
	v_mul_f32_e32 v40, 0xbfb8aa3b, v40
	v_mul_f32_e32 v41, 0xbfb8aa3b, v41
	v_mul_f32_e32 v34, v34, v62
	v_mul_f32_e32 v35, v35, v62
	v_rcp_f32_e32 v46, v46
	v_rcp_f32_e32 v47, v47
	v_add_f32_e32 v48, 1.0, v48
	v_add_f32_e32 v49, 1.0, v49
	v_exp_f32_e32 v40, v40
	v_exp_f32_e32 v41, v41
	v_mul_f32_e32 v34, 0xbfb8aa3b, v34
	v_mul_f32_e32 v35, 0xbfb8aa3b, v35
	v_rcp_f32_e32 v48, v48
	v_rcp_f32_e32 v49, v49
	v_add_f32_e32 v42, 1.0, v42
	v_add_f32_e32 v43, 1.0, v43
	v_exp_f32_e32 v34, v34
	v_exp_f32_e32 v35, v35
	v_rcp_f32_e32 v42, v42
	v_rcp_f32_e32 v43, v43
	v_add_f32_e32 v44, 1.0, v44
	v_add_f32_e32 v45, 1.0, v45
	v_lshlrev_b32_e32 v50, 16, v78
	v_and_b32_e32 v51, 0xffff0000, v78
	v_rcp_f32_e32 v44, v44
	v_rcp_f32_e32 v45, v45
	v_add_f32_e32 v38, 1.0, v38
	v_add_f32_e32 v39, 1.0, v39
	v_pk_fma_f32 v[46:47], v[46:47], v[52:53], v[50:51]
	v_lshlrev_b32_e32 v50, 16, v79
	v_and_b32_e32 v51, 0xffff0000, v79
	v_lshlrev_b32_e32 v52, 16, v75
	v_and_b32_e32 v53, 0xffff0000, v75
	v_rcp_f32_e32 v38, v38
	v_rcp_f32_e32 v39, v39
	v_add_f32_e32 v40, 1.0, v40
	v_add_f32_e32 v41, 1.0, v41
	v_mul_f32_e32 v36, v36, v62
	v_mul_f32_e32 v37, v37, v62
	v_pk_fma_f32 v[48:49], v[48:49], v[52:53], v[50:51]
	v_lshlrev_b32_e32 v50, 16, v80
	v_and_b32_e32 v51, 0xffff0000, v80
	v_lshlrev_b32_e32 v52, 16, v76
	v_and_b32_e32 v53, 0xffff0000, v76
	v_rcp_f32_e32 v40, v40
	v_rcp_f32_e32 v41, v41
	v_add_f32_e32 v34, 1.0, v34
	v_add_f32_e32 v35, 1.0, v35
	v_mul_f32_e32 v36, 0xbfb8aa3b, v36
	v_mul_f32_e32 v37, 0xbfb8aa3b, v37
	v_pk_fma_f32 v[42:43], v[42:43], v[52:53], v[50:51]
	v_lshlrev_b32_e32 v50, 16, v81
	v_and_b32_e32 v51, 0xffff0000, v81
	v_lshlrev_b32_e32 v52, 16, v77
	v_and_b32_e32 v53, 0xffff0000, v77
	v_rcp_f32_e32 v34, v34
	v_rcp_f32_e32 v35, v35
	v_exp_f32_e32 v36, v36
	v_exp_f32_e32 v37, v37
	v_pk_fma_f32 v[44:45], v[44:45], v[52:53], v[50:51]
	v_lshlrev_b32_e32 v50, 16, v70
	v_and_b32_e32 v51, 0xffff0000, v70
	v_lshlrev_b32_e32 v52, 16, v66
	v_and_b32_e32 v53, 0xffff0000, v66
	v_pk_fma_f32 v[38:39], v[38:39], v[52:53], v[50:51]
	v_lshlrev_b32_e32 v50, 16, v71
	v_and_b32_e32 v51, 0xffff0000, v71
	v_lshlrev_b32_e32 v52, 16, v67
	v_and_b32_e32 v53, 0xffff0000, v67
	v_pk_fma_f32 v[40:41], v[40:41], v[52:53], v[50:51]
	v_lshlrev_b32_e32 v50, 16, v72
	v_and_b32_e32 v51, 0xffff0000, v72
	v_lshlrev_b32_e32 v52, 16, v68
	v_and_b32_e32 v53, 0xffff0000, v68
	v_pk_fma_f32 v[50:51], v[34:35], v[52:53], v[50:51]
	v_add_f32_e32 v34, 1.0, v36
	v_add_f32_e32 v35, 1.0, v37
	v_rcp_f32_e32 v34, v34
	v_rcp_f32_e32 v35, v35
	v_lshlrev_b32_e32 v36, 16, v73
	v_and_b32_e32 v37, 0xffff0000, v73
	v_lshlrev_b32_e32 v52, 16, v69
	v_and_b32_e32 v53, 0xffff0000, v69
	v_pk_fma_f32 v[52:53], v[34:35], v[52:53], v[36:37]
	v_pk_mul_f32 v[34:35], v[38:39], v[38:39]
	v_pk_mul_f32 v[36:37], v[40:41], v[40:41]
	v_pk_mul_f32 v[58:59], v[42:43], v[42:43]
	v_pk_mul_f32 v[60:61], v[44:45], v[44:45]
	v_add_f32_e32 v36, v36, v37
	v_add_f32_e32 v34, v34, v35
	v_pk_mul_f32 v[54:55], v[46:47], v[46:47]
	v_pk_mul_f32 v[56:57], v[48:49], v[48:49]
	v_pk_mul_f32 v[62:63], v[50:51], v[50:51]
	v_pk_mul_f32 v[64:65], v[52:53], v[52:53]
	v_add_f32_e32 v34, v34, v36
	v_add_f32_e32 v35, v60, v61
	v_add_f32_e32 v36, v58, v59
	v_add_f32_e32 v64, v64, v65
	v_add_f32_e32 v62, v62, v63
	v_add_f32_e32 v35, v36, v35
	v_add_f32_e32 v36, v56, v57
	v_add_f32_e32 v37, v54, v55
	v_add_f32_e32 v62, v62, v64
	v_add_f32_e32 v36, v37, v36
	v_add_f32_e32 v34, v34, v62
	v_add_f32_e32 v35, v36, v35
	v_add_f32_e32 v54, v35, v34
	ds_bpermute_b32 v55, v188, v54
	v_lshlrev_b64 v[34:35], 10, v[108:109]
	v_lshl_add_u64 v[34:35], v[34:35], 2, s[74:75]
	v_lshl_add_u64 v[36:37], v[172:173], 2, v[34:35]
	global_store_dwordx4 v[36:37], v[46:49], off
	global_store_dwordx4 v[36:37], v[42:45], off offset:16
	global_store_dwordx4 v[36:37], v[38:41], off offset:512
	global_store_dwordx4 v[36:37], v[50:53], off offset:528
	s_waitcnt lgkmcnt(0)
	v_add_f32_e32 v34, v54, v55
	ds_bpermute_b32 v35, v170, v34
	s_and_saveexec_b64 s[0:1], vcc
	s_cbranch_execz .LBB0_727
	v_lshl_add_u64 v[36:37], s[6:7], 0, v[106:107]
	s_lshl_b32 s12, s34, 2
	v_lshl_add_u64 v[36:37], v[36:37], 0, s[12:13]
	s_waitcnt lgkmcnt(0)
	v_add_f32_e32 v34, v34, v35
	global_store_dword v[36:37], v34, off
.LBB0_727:
	s_or_b64 exec, exec, s[0:1]
	v_add_u32_e32 v80, 0xa0, v174
	v_ashrrev_i32_e32 v81, 31, v80
	v_lshlrev_b64 v[78:79], 6, v[80:81]
	s_waitcnt lgkmcnt(0)
	v_lshl_add_u64 v[34:35], s[8:9], 0, v[78:79]
	global_load_dwordx4 v[82:85], v[34:35], off
	global_load_dwordx4 v[86:89], v[34:35], off offset:32
	global_load_dwordx4 v[90:93], v[34:35], off offset:16
	global_load_dwordx4 v[94:97], v[34:35], off offset:48
	v_lshlrev_b64 v[34:35], 11, v[80:81]
	v_lshl_add_u64 v[36:37], s[2:3], 0, v[34:35]
	v_lshl_add_u64 v[36:37], v[36:37], 0, v[176:177]
	global_load_dwordx4 v[98:101], v[36:37], off
	v_lshl_add_u64 v[34:35], s[10:11], 0, v[34:35]
	v_lshl_add_u64 v[34:35], v[34:35], 0, v[176:177]
	global_load_dwordx4 v[102:105], v[34:35], off
	v_add_u32_e32 v76, 0xb0, v174
	v_ashrrev_i32_e32 v77, 31, v76
	v_lshlrev_b64 v[74:75], 6, v[76:77]
	v_lshlrev_b64 v[38:39], 11, v[76:77]
	v_lshl_add_u64 v[40:41], s[8:9], 0, v[74:75]
	v_lshl_add_u64 v[42:43], s[2:3], 0, v[38:39]
	v_lshl_add_u64 v[38:39], s[10:11], 0, v[38:39]
	global_load_dwordx4 v[50:53], v[40:41], off offset:48
	global_load_dwordx4 v[58:61], v[40:41], off offset:32
	global_load_dwordx4 v[62:65], v[40:41], off offset:16
	global_load_dwordx4 v[54:57], v[40:41], off
	v_lshl_add_u64 v[40:41], v[42:43], 0, v[176:177]
	v_lshl_add_u64 v[106:107], v[38:39], 0, v[176:177]
	global_load_dwordx4 v[70:73], v[36:37], off offset:256
	global_load_dwordx4 v[66:69], v[34:35], off offset:256
	global_load_dwordx4 v[46:49], v[40:41], off
	s_nop 0
	global_load_dwordx4 v[38:41], v[40:41], off offset:256
	s_nop 0
	global_load_dwordx4 v[42:45], v[106:107], off
	global_load_dwordx4 v[34:37], v[106:107], off offset:256
	s_waitcnt vmcnt(15)
	v_mov_b32_e32 v106, v84
	s_waitcnt vmcnt(14)
	v_mov_b32_e32 v107, v88
	v_mov_b32_e32 v88, v85
	s_waitcnt vmcnt(13)
	v_mov_b32_e32 v84, v90
	s_waitcnt vmcnt(12)
	v_mov_b32_e32 v85, v94
	v_mov_b32_e32 v94, v91
	v_mov_b32_e32 v90, v92
	v_mov_b32_e32 v91, v96
	v_mov_b32_e32 v96, v93
	v_mov_b32_e32 v92, v82
	v_mov_b32_e32 v93, v86
	v_mov_b32_e32 v86, v83
	v_pk_add_f32 v[82:83], v[106:107], v[88:89]
	v_pk_add_f32 v[84:85], v[84:85], v[94:95]
	v_pk_add_f32 v[88:89], v[90:91], v[96:97]
	v_pk_add_f32 v[86:87], v[92:93], v[86:87]
	v_pk_add_f32 v[84:85], v[84:85], v[88:89]
	v_pk_add_f32 v[82:83], v[86:87], v[82:83]
	s_waitcnt vmcnt(11)
	v_lshlrev_b32_e32 v90, 16, v98
	v_pk_add_f32 v[82:83], v[82:83], v[84:85]
	v_and_b32_e32 v91, 0xffff0000, v98
	v_add_f32_e32 v82, v82, v83
	v_fmamk_f32 v82, v82, 0x3a800000, v186
	v_mul_f32_e32 v83, 0x4b800000, v82
	v_cmp_gt_f32_e64 s[0:1], s45, v82
	v_lshlrev_b32_e32 v94, 16, v99
	v_and_b32_e32 v95, 0xffff0000, v99
	v_cndmask_b32_e64 v82, v82, v83, s[0:1]
	v_rsq_f32_e32 v84, v82
	v_lshlrev_b32_e32 v98, 16, v100
	v_and_b32_e32 v99, 0xffff0000, v100
	s_waitcnt vmcnt(10)
	v_lshlrev_b32_e32 v92, 16, v102
	v_mul_f32_e32 v85, 0x45800000, v84
	v_cndmask_b32_e64 v100, v84, v85, s[0:1]
	v_mul_f32_e32 v30, v30, v100
	v_mul_f32_e32 v31, v31, v100
	v_mul_f32_e32 v32, v32, v100
	v_mul_f32_e32 v33, v33, v100
	v_mul_f32_e32 v26, v26, v100
	v_mul_f32_e32 v27, v27, v100
	v_mul_f32_e32 v29, v29, v100
	v_mul_f32_e32 v30, 0xbfb8aa3b, v30
	v_mul_f32_e32 v31, 0xbfb8aa3b, v31
	v_mul_f32_e32 v24, v24, v100
	v_mul_f32_e32 v25, v25, v100
	v_mul_f32_e32 v32, 0xbfb8aa3b, v32
	v_mul_f32_e32 v33, 0xbfb8aa3b, v33
	v_mul_f32_e32 v26, 0xbfb8aa3b, v26
	v_mul_f32_e32 v27, 0xbfb8aa3b, v27
	v_mul_f32_e32 v84, 0xbfb8aa3b, v29
	v_exp_f32_e32 v29, v30
	v_exp_f32_e32 v30, v31
	v_mul_f32_e32 v24, 0xbfb8aa3b, v24
	v_mul_f32_e32 v25, 0xbfb8aa3b, v25
	v_mul_f32_e32 v18, v18, v100
	v_mul_f32_e32 v19, v19, v100
	v_exp_f32_e32 v31, v32
	v_exp_f32_e32 v32, v33
	v_exp_f32_e32 v26, v26
	v_exp_f32_e32 v27, v27
	v_exp_f32_e32 v24, v24
	v_exp_f32_e32 v25, v25
	v_mul_f32_e32 v18, 0xbfb8aa3b, v18
	v_mul_f32_e32 v19, 0xbfb8aa3b, v19
	v_mul_f32_e32 v28, v28, v100
	v_exp_f32_e32 v18, v18
	v_exp_f32_e32 v19, v19
	v_mul_f32_e32 v28, 0xbfb8aa3b, v28
	v_exp_f32_e32 v33, v28
	v_add_f32_e32 v28, 1.0, v29
	v_add_f32_e32 v29, 1.0, v30
	v_mul_f32_e32 v22, v22, v100
	v_mul_f32_e32 v23, v23, v100
	v_add_f32_e32 v30, 1.0, v31
	v_add_f32_e32 v31, 1.0, v32
	v_add_f32_e32 v32, 1.0, v26
	v_add_f32_e32 v85, 1.0, v27
	v_rcp_f32_e32 v26, v28
	v_rcp_f32_e32 v27, v29
	v_mul_f32_e32 v22, 0xbfb8aa3b, v22
	v_mul_f32_e32 v23, 0xbfb8aa3b, v23
	v_add_f32_e32 v24, 1.0, v24
	v_add_f32_e32 v25, 1.0, v25
	v_mul_f32_e32 v20, v20, v100
	v_mul_f32_e32 v21, v21, v100
	v_exp_f32_e32 v22, v22
	v_exp_f32_e32 v23, v23
	v_rcp_f32_e32 v24, v24
	v_rcp_f32_e32 v25, v25
	v_add_f32_e32 v18, 1.0, v18
	v_add_f32_e32 v19, 1.0, v19
	v_mul_f32_e32 v20, 0xbfb8aa3b, v20
	v_mul_f32_e32 v21, 0xbfb8aa3b, v21
	v_exp_f32_e32 v84, v84
	v_rcp_f32_e32 v18, v18
	v_rcp_f32_e32 v19, v19
	v_exp_f32_e32 v20, v20
	v_exp_f32_e32 v21, v21
	v_and_b32_e32 v93, 0xffff0000, v102
	v_pk_fma_f32 v[26:27], v[26:27], v[92:93], v[90:91]
	s_waitcnt vmcnt(5)
	v_lshlrev_b32_e32 v90, 16, v70
	v_and_b32_e32 v91, 0xffff0000, v70
	s_waitcnt vmcnt(4)
	v_lshlrev_b32_e32 v92, 16, v66
	v_and_b32_e32 v93, 0xffff0000, v66
	v_lshlrev_b32_e32 v70, 16, v71
	v_and_b32_e32 v71, 0xffff0000, v71
	v_lshlrev_b32_e32 v66, 16, v67
	v_and_b32_e32 v67, 0xffff0000, v67
	v_add_f32_e32 v22, 1.0, v22
	v_add_f32_e32 v23, 1.0, v23
	v_pk_fma_f32 v[24:25], v[24:25], v[66:67], v[70:71]
	v_lshlrev_b32_e32 v66, 16, v72
	v_and_b32_e32 v67, 0xffff0000, v72
	v_lshlrev_b32_e32 v70, 16, v68
	v_and_b32_e32 v71, 0xffff0000, v68
	v_rcp_f32_e32 v28, v30
	v_rcp_f32_e32 v29, v31
	v_rcp_f32_e32 v30, v32
	v_rcp_f32_e32 v31, v85
	v_add_f32_e32 v32, 1.0, v33
	v_add_f32_e32 v33, 1.0, v84
	v_rcp_f32_e32 v22, v22
	v_rcp_f32_e32 v23, v23
	v_pk_fma_f32 v[66:67], v[18:19], v[70:71], v[66:67]
	v_add_f32_e32 v18, 1.0, v20
	v_add_f32_e32 v19, 1.0, v21
	v_rcp_f32_e32 v32, v32
	v_rcp_f32_e32 v33, v33
	v_rcp_f32_e32 v18, v18
	v_rcp_f32_e32 v19, v19
	v_lshlrev_b32_e32 v82, 16, v104
	v_and_b32_e32 v83, 0xffff0000, v104
	v_pk_fma_f32 v[30:31], v[30:31], v[82:83], v[98:99]
	v_lshlrev_b32_e32 v82, 16, v101
	v_and_b32_e32 v83, 0xffff0000, v101
	v_lshlrev_b32_e32 v84, 16, v105
	v_and_b32_e32 v85, 0xffff0000, v105
	v_pk_fma_f32 v[22:23], v[22:23], v[92:93], v[90:91]
	v_lshlrev_b32_e32 v20, 16, v73
	v_and_b32_e32 v21, 0xffff0000, v73
	v_lshlrev_b32_e32 v68, 16, v69
	v_and_b32_e32 v69, 0xffff0000, v69
	v_lshlrev_b32_e32 v96, 16, v103
	v_and_b32_e32 v97, 0xffff0000, v103
	v_pk_fma_f32 v[32:33], v[32:33], v[84:85], v[82:83]
	v_pk_fma_f32 v[68:69], v[18:19], v[68:69], v[20:21]
	v_pk_mul_f32 v[18:19], v[22:23], v[22:23]
	v_pk_mul_f32 v[20:21], v[24:25], v[24:25]
	v_pk_fma_f32 v[28:29], v[28:29], v[96:97], v[94:95]
	v_pk_mul_f32 v[86:87], v[30:31], v[30:31]
	v_pk_mul_f32 v[88:89], v[32:33], v[32:33]
	v_add_f32_e32 v20, v20, v21
	v_add_f32_e32 v18, v18, v19
	v_pk_mul_f32 v[82:83], v[26:27], v[26:27]
	v_pk_mul_f32 v[84:85], v[28:29], v[28:29]
	v_pk_mul_f32 v[70:71], v[66:67], v[66:67]
	v_pk_mul_f32 v[72:73], v[68:69], v[68:69]
	v_add_f32_e32 v18, v18, v20
	v_add_f32_e32 v19, v88, v89
	v_add_f32_e32 v20, v86, v87
	v_add_f32_e32 v72, v72, v73
	v_add_f32_e32 v70, v70, v71
	v_add_f32_e32 v19, v20, v19
	v_add_f32_e32 v20, v84, v85
	v_add_f32_e32 v21, v82, v83
	v_add_f32_e32 v70, v70, v72
	v_add_f32_e32 v20, v21, v20
	v_add_f32_e32 v18, v18, v70
	v_add_f32_e32 v19, v20, v19
	v_add_f32_e32 v70, v19, v18
	ds_bpermute_b32 v71, v188, v70
	v_lshlrev_b64 v[18:19], 12, v[80:81]
	v_lshl_add_u64 v[18:19], s[74:75], 0, v[18:19]
	v_lshl_add_u64 v[20:21], v[172:173], 2, v[18:19]
	s_waitcnt vmcnt(0)
	global_store_dwordx4 v[20:21], v[26:29], off
	global_store_dwordx4 v[20:21], v[30:33], off offset:16
	global_store_dwordx4 v[20:21], v[22:25], off offset:512
	global_store_dwordx4 v[20:21], v[66:69], off offset:528
	s_waitcnt lgkmcnt(0)
	v_add_f32_e32 v18, v70, v71
	ds_bpermute_b32 v19, v170, v18
	s_and_saveexec_b64 s[0:1], vcc
	s_cbranch_execz .LBB0_729
	v_lshl_add_u64 v[20:21], s[6:7], 0, v[78:79]
	s_lshl_b32 s12, s34, 2
	v_lshl_add_u64 v[20:21], v[20:21], 0, s[12:13]
	s_waitcnt lgkmcnt(0)
	v_add_f32_e32 v18, v18, v19
	global_store_dword v[20:21], v18, off
.LBB0_729:
	s_or_b64 exec, exec, s[0:1]
	s_waitcnt lgkmcnt(0)
	v_add_f32_e32 v19, v62, v63
	v_add_f32_e32 v20, v64, v65
	v_add_f32_e32 v19, v19, v20
	v_add_f32_e32 v20, v58, v59
	v_add_f32_e32 v21, v60, v61
	v_add_f32_e32 v20, v20, v21
	v_add_f32_e32 v21, v50, v51
	v_add_f32_e32 v22, v52, v53
	v_add_f32_e32 v21, v21, v22
	v_add_f32_e32 v18, v56, v57
	v_add_f32_e32 v20, v20, v21
	v_add_f32_e32 v21, v54, v55
	v_add_f32_e32 v18, v21, v18
	v_add_f32_e32 v18, v18, v19
	v_add_f32_e32 v18, v18, v20
	v_fmamk_f32 v18, v18, 0x3a800000, v186
	v_mul_f32_e32 v19, 0x4b800000, v18
	v_cmp_gt_f32_e64 s[0:1], s45, v18
	v_lshlrev_b32_e32 v20, 16, v42
	v_and_b32_e32 v21, 0xffff0000, v42
	v_cndmask_b32_e64 v18, v18, v19, s[0:1]
	v_rsq_f32_e32 v18, v18
	s_nop 0
	v_mul_f32_e32 v19, 0x45800000, v18
	v_cndmask_b32_e64 v30, v18, v19, s[0:1]
	v_mul_f32_e32 v14, v14, v30
	v_mul_f32_e32 v15, v15, v30
	v_mul_f32_e32 v14, 0xbfb8aa3b, v14
	v_mul_f32_e32 v15, 0xbfb8aa3b, v15
	v_mul_f32_e32 v16, v16, v30
	v_mul_f32_e32 v17, v17, v30
	v_exp_f32_e32 v14, v14
	v_exp_f32_e32 v15, v15
	v_mul_f32_e32 v16, 0xbfb8aa3b, v16
	v_mul_f32_e32 v17, 0xbfb8aa3b, v17
	v_mul_f32_e32 v10, v10, v30
	v_mul_f32_e32 v11, v11, v30
	v_exp_f32_e32 v16, v16
	v_exp_f32_e32 v17, v17
	v_mul_f32_e32 v10, 0xbfb8aa3b, v10
	v_mul_f32_e32 v11, 0xbfb8aa3b, v11
	v_mul_f32_e32 v12, v12, v30
	v_mul_f32_e32 v13, v13, v30
	v_exp_f32_e32 v10, v10
	v_exp_f32_e32 v11, v11
	v_mul_f32_e32 v12, 0xbfb8aa3b, v12
	v_mul_f32_e32 v13, 0xbfb8aa3b, v13
	v_mul_f32_e32 v6, v6, v30
	v_mul_f32_e32 v7, v7, v30
	v_exp_f32_e32 v12, v12
	v_exp_f32_e32 v13, v13
	v_mul_f32_e32 v6, 0xbfb8aa3b, v6
	v_mul_f32_e32 v7, 0xbfb8aa3b, v7
	v_mul_f32_e32 v8, v8, v30
	v_mul_f32_e32 v9, v9, v30
	v_add_f32_e32 v14, 1.0, v14
	v_add_f32_e32 v15, 1.0, v15
	v_exp_f32_e32 v6, v6
	v_exp_f32_e32 v7, v7
	v_mul_f32_e32 v8, 0xbfb8aa3b, v8
	v_mul_f32_e32 v9, 0xbfb8aa3b, v9
	v_mul_f32_e32 v2, v2, v30
	v_mul_f32_e32 v3, v3, v30
	v_rcp_f32_e32 v14, v14
	v_rcp_f32_e32 v15, v15
	v_add_f32_e32 v16, 1.0, v16
	v_add_f32_e32 v17, 1.0, v17
	v_exp_f32_e32 v8, v8
	v_exp_f32_e32 v9, v9
	v_mul_f32_e32 v2, 0xbfb8aa3b, v2
	v_mul_f32_e32 v3, 0xbfb8aa3b, v3
	v_rcp_f32_e32 v16, v16
	v_rcp_f32_e32 v17, v17
	v_add_f32_e32 v10, 1.0, v10
	v_add_f32_e32 v11, 1.0, v11
	v_exp_f32_e32 v2, v2
	v_exp_f32_e32 v3, v3
	v_rcp_f32_e32 v10, v10
	v_rcp_f32_e32 v11, v11
	v_add_f32_e32 v12, 1.0, v12
	v_add_f32_e32 v13, 1.0, v13
	v_lshlrev_b32_e32 v18, 16, v46
	v_and_b32_e32 v19, 0xffff0000, v46
	v_rcp_f32_e32 v12, v12
	v_rcp_f32_e32 v13, v13
	v_add_f32_e32 v6, 1.0, v6
	v_add_f32_e32 v7, 1.0, v7
	v_pk_fma_f32 v[14:15], v[14:15], v[20:21], v[18:19]
	v_lshlrev_b32_e32 v18, 16, v47
	v_and_b32_e32 v19, 0xffff0000, v47
	v_lshlrev_b32_e32 v20, 16, v43
	v_and_b32_e32 v21, 0xffff0000, v43
	v_rcp_f32_e32 v6, v6
	v_rcp_f32_e32 v7, v7
	v_add_f32_e32 v8, 1.0, v8
	v_add_f32_e32 v9, 1.0, v9
	v_mul_f32_e32 v4, v4, v30
	v_mul_f32_e32 v5, v5, v30
	v_pk_fma_f32 v[16:17], v[16:17], v[20:21], v[18:19]
	v_lshlrev_b32_e32 v18, 16, v48
	v_and_b32_e32 v19, 0xffff0000, v48
	v_lshlrev_b32_e32 v20, 16, v44
	v_and_b32_e32 v21, 0xffff0000, v44
	v_rcp_f32_e32 v8, v8
	v_rcp_f32_e32 v9, v9
	v_add_f32_e32 v2, 1.0, v2
	v_add_f32_e32 v3, 1.0, v3
	v_mul_f32_e32 v4, 0xbfb8aa3b, v4
	v_mul_f32_e32 v5, 0xbfb8aa3b, v5
	v_pk_fma_f32 v[10:11], v[10:11], v[20:21], v[18:19]
	v_lshlrev_b32_e32 v18, 16, v49
	v_and_b32_e32 v19, 0xffff0000, v49
	v_lshlrev_b32_e32 v20, 16, v45
	v_and_b32_e32 v21, 0xffff0000, v45
	v_rcp_f32_e32 v2, v2
	v_rcp_f32_e32 v3, v3
	v_exp_f32_e32 v4, v4
	v_exp_f32_e32 v5, v5
	v_pk_fma_f32 v[12:13], v[12:13], v[20:21], v[18:19]
	v_lshlrev_b32_e32 v18, 16, v38
	v_and_b32_e32 v19, 0xffff0000, v38
	v_lshlrev_b32_e32 v20, 16, v34
	v_and_b32_e32 v21, 0xffff0000, v34
	v_pk_fma_f32 v[6:7], v[6:7], v[20:21], v[18:19]
	v_lshlrev_b32_e32 v18, 16, v39
	v_and_b32_e32 v19, 0xffff0000, v39
	v_lshlrev_b32_e32 v20, 16, v35
	v_and_b32_e32 v21, 0xffff0000, v35
	v_pk_fma_f32 v[8:9], v[8:9], v[20:21], v[18:19]
	v_lshlrev_b32_e32 v18, 16, v40
	v_and_b32_e32 v19, 0xffff0000, v40
	v_lshlrev_b32_e32 v20, 16, v36
	v_and_b32_e32 v21, 0xffff0000, v36
	v_pk_fma_f32 v[18:19], v[2:3], v[20:21], v[18:19]
	v_add_f32_e32 v2, 1.0, v4
	v_add_f32_e32 v3, 1.0, v5
	v_rcp_f32_e32 v2, v2
	v_rcp_f32_e32 v3, v3
	v_lshlrev_b32_e32 v4, 16, v41
	v_and_b32_e32 v5, 0xffff0000, v41
	v_lshlrev_b32_e32 v20, 16, v37
	v_and_b32_e32 v21, 0xffff0000, v37
	v_pk_fma_f32 v[20:21], v[2:3], v[20:21], v[4:5]
	v_pk_mul_f32 v[2:3], v[6:7], v[6:7]
	v_pk_mul_f32 v[4:5], v[8:9], v[8:9]
	v_pk_mul_f32 v[26:27], v[10:11], v[10:11]
	v_pk_mul_f32 v[28:29], v[12:13], v[12:13]
	v_add_f32_e32 v4, v4, v5
	v_add_f32_e32 v2, v2, v3
	v_pk_mul_f32 v[22:23], v[14:15], v[14:15]
	v_pk_mul_f32 v[24:25], v[16:17], v[16:17]
	v_pk_mul_f32 v[30:31], v[18:19], v[18:19]
	v_pk_mul_f32 v[32:33], v[20:21], v[20:21]
	v_add_f32_e32 v2, v2, v4
	v_add_f32_e32 v3, v28, v29
	v_add_f32_e32 v4, v26, v27
	v_add_f32_e32 v32, v32, v33
	v_add_f32_e32 v30, v30, v31
	v_add_f32_e32 v3, v4, v3
	v_add_f32_e32 v4, v24, v25
	v_add_f32_e32 v5, v22, v23
	v_add_f32_e32 v30, v30, v32
	v_add_f32_e32 v4, v5, v4
	v_add_f32_e32 v2, v2, v30
	v_add_f32_e32 v3, v4, v3
	v_add_f32_e32 v22, v3, v2
	ds_bpermute_b32 v23, v188, v22
	v_lshlrev_b64 v[2:3], 10, v[76:77]
	v_lshl_add_u64 v[2:3], v[2:3], 2, s[74:75]
	v_lshl_add_u64 v[4:5], v[172:173], 2, v[2:3]
	global_store_dwordx4 v[4:5], v[14:17], off
	global_store_dwordx4 v[4:5], v[10:13], off offset:16
	global_store_dwordx4 v[4:5], v[6:9], off offset:512
	global_store_dwordx4 v[4:5], v[18:21], off offset:528
	s_waitcnt lgkmcnt(0)
	v_add_f32_e32 v2, v22, v23
	ds_bpermute_b32 v3, v170, v2
	s_and_saveexec_b64 s[0:1], vcc
	s_cbranch_execz .LBB0_704
	v_lshl_add_u64 v[4:5], s[6:7], 0, v[74:75]
	s_lshl_b32 s12, s34, 2
	v_lshl_add_u64 v[4:5], v[4:5], 0, s[12:13]
	s_waitcnt lgkmcnt(0)
	v_add_f32_e32 v2, v2, v3
	global_store_dword v[4:5], v2, off
	s_branch .LBB0_704
